# attention epilogue: gate-load waits counted with the write-through stores in between (no store drain); ticket read deferred
# baseline (speedup 1.0000x reference)
.LBB0_499:
	v_lshlrev_b32_e32 v2, 3, v87
	v_lshlrev_b32_e32 v2, 1, v2
	v_lshl_add_u64 v[56:57], s[14:15], 0, v[2:3]
	v_lshl_add_u64 v[64:65], v[56:57], 0, s[18:19]
	v_lshl_add_u64 v[10:11], v[64:65], 0, v[10:11]
	global_load_dwordx4 v[56:59], v[10:11], off
	v_lshl_add_u64 v[10:11], v[64:65], 0, v[14:15]
	global_load_dwordx4 v[60:63], v[10:11], off
	v_pk_mul_f32 v[10:11], v[36:37], v[54:55] op_sel_hi:[1,0]
	v_pk_mul_f32 v[14:15], v[38:39], v[54:55] op_sel_hi:[1,0]
	v_pk_mul_f32 v[20:21], v[20:21], v[54:55] op_sel_hi:[1,0]
	v_pk_mul_f32 v[22:23], v[22:23], v[54:55] op_sel_hi:[1,0]
	v_cvt_pk_bf16_f32 v10, v10, v11
	v_cvt_pk_bf16_f32 v11, v14, v15
	v_cvt_pk_bf16_f32 v14, v20, v21
	v_lshl_add_u64 v[20:21], v[64:65], 0, v[52:53]
	v_cvt_pk_bf16_f32 v15, v22, v23
	global_load_dwordx4 v[20:23], v[20:21], off
	v_pk_mul_f32 v[36:37], v[40:41], v[54:55] op_sel_hi:[1,0]
	v_pk_mul_f32 v[38:39], v[42:43], v[54:55] op_sel_hi:[1,0]
	v_add_u32_e32 v19, 0x1000, v86
	v_pk_mul_f32 v[24:25], v[24:25], v[54:55] op_sel_hi:[1,0]
	v_pk_mul_f32 v[26:27], v[26:27], v[54:55] op_sel_hi:[1,0]
	v_pk_mul_f32 v[40:41], v[44:45], v[54:55] op_sel_hi:[1,0]
	v_pk_mul_f32 v[42:43], v[46:47], v[54:55] op_sel_hi:[1,0]
	v_pk_mul_f32 v[28:29], v[28:29], v[54:55] op_sel_hi:[1,0]
	v_pk_mul_f32 v[30:31], v[30:31], v[54:55] op_sel_hi:[1,0]
	v_pk_mul_f32 v[44:45], v[48:49], v[54:55] op_sel_hi:[1,0]
	v_pk_mul_f32 v[46:47], v[50:51], v[54:55] op_sel_hi:[1,0]
	v_pk_mul_f32 v[32:33], v[32:33], v[54:55] op_sel_hi:[1,0]
	v_pk_mul_f32 v[34:35], v[34:35], v[54:55] op_sel_hi:[1,0]
	v_cvt_pk_bf16_f32 v36, v36, v37
	v_cvt_pk_bf16_f32 v37, v38, v39
	v_cvt_pk_bf16_f32 v24, v24, v25
	v_cvt_pk_bf16_f32 v25, v26, v27
	v_cvt_pk_bf16_f32 v26, v40, v41
	v_cvt_pk_bf16_f32 v27, v42, v43
	v_cvt_pk_bf16_f32 v28, v28, v29
	v_cvt_pk_bf16_f32 v29, v30, v31
	v_cvt_pk_bf16_f32 v30, v44, v45
	v_cvt_pk_bf16_f32 v31, v46, v47
	v_cvt_pk_bf16_f32 v32, v32, v33
	v_cvt_pk_bf16_f32 v33, v34, v35
	ds_write2_b64 v19, v[10:11], v[36:37] offset0:64 offset1:66
	ds_write2_b64 v19, v[14:15], v[24:25] offset0:72 offset1:74
	ds_write2_b64 v19, v[26:27], v[30:31] offset0:68 offset1:70
	ds_write2_b64 v19, v[28:29], v[32:33] offset0:76 offset1:78
	v_lshl_add_u64 v[10:11], v[64:65], 0, v[12:13]
	global_load_dwordx4 v[10:13], v[10:11], off
	s_waitcnt lgkmcnt(0)
	ds_read_b128 v[24:27], v55 offset:4608
	v_lshl_add_u64 v[14:15], s[24:25], 0, v[2:3]
	v_lshl_add_u64 v[28:29], v[14:15], 0, s[20:21]
	v_lshl_add_u64 v[30:31], v[28:29], 0, v[16:17]
	v_lshl_add_u64 v[4:5], v[28:29], 0, v[4:5]
	s_waitcnt lgkmcnt(0)
	v_lshlrev_b32_e32 v14, 16, v24
	v_and_b32_e32 v15, 0xffff0000, v24
	v_lshlrev_b32_e32 v16, 16, v25
	v_and_b32_e32 v17, 0xffff0000, v25
	v_lshlrev_b32_e32 v24, 16, v26
	v_and_b32_e32 v25, 0xffff0000, v26
	v_lshlrev_b32_e32 v26, 16, v27
	v_and_b32_e32 v27, 0xffff0000, v27
	v_lshl_add_u64 v[8:9], v[28:29], 0, v[8:9]
	s_waitcnt vmcnt(3)
	v_lshlrev_b32_e32 v32, 16, v56
	v_and_b32_e32 v33, 0xffff0000, v56
	v_lshlrev_b32_e32 v34, 16, v57
	v_and_b32_e32 v35, 0xffff0000, v57
	v_lshlrev_b32_e32 v36, 16, v58
	v_and_b32_e32 v37, 0xffff0000, v58
	v_lshlrev_b32_e32 v38, 16, v59
	v_and_b32_e32 v39, 0xffff0000, v59
	v_pk_mul_f32 v[14:15], v[32:33], v[14:15]
	v_pk_mul_f32 v[16:17], v[34:35], v[16:17]
	v_pk_mul_f32 v[24:25], v[36:37], v[24:25]
	v_pk_mul_f32 v[26:27], v[38:39], v[26:27]
	v_cvt_pk_bf16_f32 v14, v14, v15
	v_cvt_pk_bf16_f32 v15, v16, v17
	v_cvt_pk_bf16_f32 v16, v24, v25
	v_cvt_pk_bf16_f32 v17, v26, v27
	global_store_dwordx4 v[30:31], v[14:17], off sc0 sc1
	s_nop 1
	ds_read_b128 v[14:17], v55 offset:5760
	s_waitcnt vmcnt(3)
	v_lshlrev_b32_e32 v24, 16, v61
	v_and_b32_e32 v25, 0xffff0000, v61
	v_lshlrev_b32_e32 v26, 16, v62
	v_and_b32_e32 v27, 0xffff0000, v62
	s_waitcnt lgkmcnt(0)
	v_lshlrev_b32_e32 v30, 16, v14
	v_and_b32_e32 v31, 0xffff0000, v14
	v_lshlrev_b32_e32 v14, 16, v15
	v_and_b32_e32 v15, 0xffff0000, v15
	v_lshlrev_b32_e32 v32, 16, v16
	v_and_b32_e32 v33, 0xffff0000, v16
	v_pk_mul_f32 v[24:25], v[24:25], v[14:15]
	v_lshlrev_b32_e32 v40, 16, v60
	v_cvt_pk_bf16_f32 v15, v24, v25
	v_pk_mul_f32 v[24:25], v[26:27], v[32:33]
	v_and_b32_e32 v41, 0xffff0000, v60
	v_cvt_pk_bf16_f32 v16, v24, v25
	v_lshlrev_b32_e32 v24, 16, v17
	v_and_b32_e32 v25, 0xffff0000, v17
	v_lshlrev_b32_e32 v26, 16, v63
	v_and_b32_e32 v27, 0xffff0000, v63
	v_pk_mul_f32 v[30:31], v[40:41], v[30:31]
	v_pk_mul_f32 v[24:25], v[26:27], v[24:25]
	v_cvt_pk_bf16_f32 v14, v30, v31
	v_cvt_pk_bf16_f32 v17, v24, v25
	global_store_dwordx4 v[4:5], v[14:17], off sc0 sc1
	s_nop 1
	ds_read_b128 v[14:17], v55 offset:6912
	s_waitcnt vmcnt(3)
	v_lshlrev_b32_e32 v24, 16, v20
	v_and_b32_e32 v25, 0xffff0000, v20
	v_lshlrev_b32_e32 v20, 16, v21
	v_and_b32_e32 v21, 0xffff0000, v21
	s_waitcnt lgkmcnt(0)
	v_lshlrev_b32_e32 v4, 16, v14
	v_and_b32_e32 v5, 0xffff0000, v14
	v_pk_mul_f32 v[4:5], v[24:25], v[4:5]
	s_nop 0
	v_cvt_pk_bf16_f32 v14, v4, v5
	v_lshlrev_b32_e32 v4, 16, v15
	v_and_b32_e32 v5, 0xffff0000, v15
	v_pk_mul_f32 v[4:5], v[20:21], v[4:5]
	v_lshlrev_b32_e32 v20, 16, v22
	v_cvt_pk_bf16_f32 v15, v4, v5
	v_lshlrev_b32_e32 v4, 16, v16
	v_and_b32_e32 v5, 0xffff0000, v16
	v_and_b32_e32 v21, 0xffff0000, v22
	v_pk_mul_f32 v[4:5], v[20:21], v[4:5]
	v_lshlrev_b32_e32 v20, 16, v23
	v_cvt_pk_bf16_f32 v16, v4, v5
	v_lshlrev_b32_e32 v4, 16, v17
	v_and_b32_e32 v5, 0xffff0000, v17
	v_and_b32_e32 v21, 0xffff0000, v23
	v_pk_mul_f32 v[4:5], v[20:21], v[4:5]
	s_nop 0
	v_cvt_pk_bf16_f32 v17, v4, v5
	v_lshl_add_u64 v[4:5], v[28:29], 0, v[6:7]
	global_store_dwordx4 v[4:5], v[14:17], off sc0 sc1
	s_nop 1
	ds_read_b128 v[4:7], v55 offset:8064
	s_waitcnt vmcnt(3)
	v_lshlrev_b32_e32 v16, 16, v10
	v_and_b32_e32 v17, 0xffff0000, v10
	v_lshlrev_b32_e32 v10, 16, v11
	v_and_b32_e32 v11, 0xffff0000, v11
	s_waitcnt lgkmcnt(0)
	v_lshlrev_b32_e32 v14, 16, v4
	v_and_b32_e32 v15, 0xffff0000, v4
	v_pk_mul_f32 v[14:15], v[16:17], v[14:15]
	s_nop 0
	v_cvt_pk_bf16_f32 v4, v14, v15
	v_lshlrev_b32_e32 v14, 16, v5
	v_and_b32_e32 v15, 0xffff0000, v5
	v_pk_mul_f32 v[10:11], v[10:11], v[14:15]
	v_lshlrev_b32_e32 v14, 16, v12
	v_cvt_pk_bf16_f32 v5, v10, v11
	v_lshlrev_b32_e32 v10, 16, v6
	v_and_b32_e32 v11, 0xffff0000, v6
	v_and_b32_e32 v15, 0xffff0000, v12
	v_pk_mul_f32 v[10:11], v[14:15], v[10:11]
	v_lshlrev_b32_e32 v12, 16, v13
	v_cvt_pk_bf16_f32 v6, v10, v11
	v_lshlrev_b32_e32 v10, 16, v7
	v_and_b32_e32 v11, 0xffff0000, v7
	v_and_b32_e32 v13, 0xffff0000, v13
	v_pk_mul_f32 v[10:11], v[12:13], v[10:11]
	s_nop 0
	v_cvt_pk_bf16_f32 v7, v10, v11
	global_store_dwordx4 v[8:9], v[4:7], off sc0 sc1
	s_nop 1

.LBB0_576:
	s_mov_b32 s25, s36
	s_waitcnt lgkmcnt(0)
	s_add_u32 s28, s26, s14
	s_addc_u32 s29, s27, s15
	s_lshl_b64 s[14:15], s[24:25], 10
	s_add_u32 s14, s28, s14
	s_addc_u32 s15, s29, s15
	s_lshl_b32 s28, s68, 1
	s_add_u32 s14, s14, s28
	v_ashrrev_i32_e32 v16, 3, v186
	v_and_b32_e32 v87, 7, v186
	s_addc_u32 s15, s15, 0
	v_lshlrev_b32_e32 v2, 4, v87
	v_ashrrev_i32_e32 v17, 31, v16
	v_lshl_add_u64 v[88:89], s[14:15], 0, v[2:3]
	v_lshlrev_b64 v[10:11], 10, v[16:17]
	v_lshl_add_u64 v[6:7], v[88:89], 0, v[10:11]
	global_load_dwordx4 v[6:9], v[6:7], off
	v_mov_b32_e32 v5, s63
	v_ashrrev_i32_e32 v12, 2, v186
	v_mad_u32_u24 v5, v188, s67, v5
	v_and_b32_e32 v12, -8, v12
	v_add_u32_e32 v86, v5, v12
	v_pk_mul_f32 v[12:13], v[52:53], v[4:5] op_sel_hi:[1,0]
	v_pk_mul_f32 v[14:15], v[54:55], v[4:5] op_sel_hi:[1,0]
	v_cvt_pk_bf16_f32 v12, v12, v13
	v_cvt_pk_bf16_f32 v13, v14, v15
	v_pk_mul_f32 v[14:15], v[68:69], v[4:5] op_sel_hi:[1,0]
	v_add_u32_e32 v90, 8, v16
	v_cvt_pk_bf16_f32 v52, v14, v15
	v_pk_mul_f32 v[14:15], v[70:71], v[4:5] op_sel_hi:[1,0]
	v_ashrrev_i32_e32 v91, 31, v90
	v_cvt_pk_bf16_f32 v53, v14, v15
	v_pk_mul_f32 v[14:15], v[56:57], v[4:5] op_sel_hi:[1,0]
	v_pk_mul_f32 v[68:69], v[58:59], v[4:5] op_sel_hi:[1,0]
	v_cvt_pk_bf16_f32 v54, v14, v15
	v_lshlrev_b64 v[14:15], 10, v[90:91]
	v_lshl_add_u64 v[56:57], v[88:89], 0, v[14:15]
	global_load_dwordx4 v[56:59], v[56:57], off
	v_cvt_pk_bf16_f32 v55, v68, v69
	ds_write2_b64 v86, v[12:13], v[54:55] offset1:2
	v_pk_mul_f32 v[12:13], v[72:73], v[4:5] op_sel_hi:[1,0]
	v_pk_mul_f32 v[54:55], v[74:75], v[4:5] op_sel_hi:[1,0]
	v_cvt_pk_bf16_f32 v12, v12, v13
	v_cvt_pk_bf16_f32 v13, v54, v55
	ds_write2_b64 v86, v[52:53], v[12:13] offset0:8 offset1:10
	v_pk_mul_f32 v[12:13], v[60:61], v[4:5] op_sel_hi:[1,0]
	v_pk_mul_f32 v[52:53], v[62:63], v[4:5] op_sel_hi:[1,0]
	v_cvt_pk_bf16_f32 v12, v12, v13
	v_cvt_pk_bf16_f32 v13, v52, v53
	v_pk_mul_f32 v[52:53], v[76:77], v[4:5] op_sel_hi:[1,0]
	v_pk_mul_f32 v[54:55], v[78:79], v[4:5] op_sel_hi:[1,0]
	v_cvt_pk_bf16_f32 v52, v52, v53
	v_cvt_pk_bf16_f32 v53, v54, v55
	v_pk_mul_f32 v[54:55], v[64:65], v[4:5] op_sel_hi:[1,0]
	v_pk_mul_f32 v[60:61], v[66:67], v[4:5] op_sel_hi:[1,0]
	v_cvt_pk_bf16_f32 v54, v54, v55
	v_cvt_pk_bf16_f32 v55, v60, v61
	ds_write2_b64 v86, v[12:13], v[54:55] offset0:4 offset1:6
	v_pk_mul_f32 v[12:13], v[80:81], v[4:5] op_sel_hi:[1,0]
	v_pk_mul_f32 v[4:5], v[82:83], v[4:5] op_sel_hi:[1,0]
	v_add_u32_e32 v72, 16, v16
	v_cvt_pk_bf16_f32 v12, v12, v13
	v_cvt_pk_bf16_f32 v13, v4, v5
	v_ashrrev_i32_e32 v73, 31, v72
	ds_write2_b64 v86, v[52:53], v[12:13] offset0:12 offset1:14
	v_lshlrev_b64 v[52:53], 10, v[72:73]
	v_lshl_add_u64 v[4:5], v[88:89], 0, v[52:53]
	global_load_dwordx4 v[60:63], v[4:5], off
	v_add_u32_e32 v74, 24, v16
	v_ashrrev_i32_e32 v75, 31, v74
	v_lshlrev_b64 v[12:13], 10, v[74:75]
	v_lshl_add_u64 v[4:5], v[88:89], 0, v[12:13]
	global_load_dwordx4 v[64:67], v[4:5], off
	s_waitcnt lgkmcnt(0)
	v_add_u32_e32 v4, s63, v2
	v_mul_lo_u32 v5, v16, s67
	v_add_u32_e32 v55, v4, v5
	s_lshl_b64 s[24:25], s[24:25], 11
	ds_read_b128 v[68:71], v55
	s_add_u32 s24, s26, s24
	s_addc_u32 s25, s27, s25
	s_lshl_b32 s26, s30, 1
	s_add_u32 s24, s24, s26
	s_addc_u32 s25, s25, 0
	s_add_u32 s24, s24, s28
	s_waitcnt lgkmcnt(0)
	v_lshlrev_b32_e32 v4, 16, v68
	v_and_b32_e32 v5, 0xffff0000, v68
	v_lshlrev_b32_e32 v68, 16, v69
	v_and_b32_e32 v69, 0xffff0000, v69
	s_addc_u32 s25, s25, 0
	s_add_u32 s24, s24, 0x5400000
	s_addc_u32 s25, s25, 0
	v_lshl_add_u64 v[76:77], s[24:25], 0, v[2:3]
	v_lshlrev_b64 v[16:17], 11, v[16:17]
	s_and_b64 vcc, exec, s[6:7]
	s_waitcnt vmcnt(3)
	v_lshlrev_b32_e32 v78, 16, v6
	v_and_b32_e32 v79, 0xffff0000, v6
	v_lshlrev_b32_e32 v6, 16, v7
	v_and_b32_e32 v7, 0xffff0000, v7
	v_pk_mul_f32 v[4:5], v[78:79], v[4:5]
	v_pk_mul_f32 v[6:7], v[6:7], v[68:69]
	v_cvt_pk_bf16_f32 v4, v4, v5
	v_cvt_pk_bf16_f32 v5, v6, v7
	v_lshlrev_b32_e32 v6, 16, v70
	v_and_b32_e32 v7, 0xffff0000, v70
	v_lshlrev_b32_e32 v68, 16, v8
	v_and_b32_e32 v69, 0xffff0000, v8
	v_pk_mul_f32 v[6:7], v[68:69], v[6:7]
	v_lshlrev_b32_e32 v68, 16, v71
	v_and_b32_e32 v69, 0xffff0000, v71
	v_lshlrev_b32_e32 v8, 16, v9
	v_and_b32_e32 v9, 0xffff0000, v9
	v_pk_mul_f32 v[8:9], v[8:9], v[68:69]
	v_cvt_pk_bf16_f32 v6, v6, v7
	v_cvt_pk_bf16_f32 v7, v8, v9
	v_lshl_add_u64 v[8:9], v[76:77], 0, v[16:17]
	global_store_dwordx4 v[8:9], v[4:7], off sc0 sc1
	s_nop 1
	ds_read_b128 v[4:7], v55 offset:1152
	s_waitcnt vmcnt(3)
	v_lshlrev_b32_e32 v68, 16, v56
	v_and_b32_e32 v69, 0xffff0000, v56
	s_waitcnt lgkmcnt(0)
	v_lshlrev_b32_e32 v8, 16, v4
	v_and_b32_e32 v9, 0xffff0000, v4
	v_pk_mul_f32 v[8:9], v[68:69], v[8:9]
	v_lshlrev_b32_e32 v4, 16, v5
	v_cvt_pk_bf16_f32 v56, v8, v9
	v_and_b32_e32 v5, 0xffff0000, v5
	v_lshlrev_b32_e32 v8, 16, v57
	v_and_b32_e32 v9, 0xffff0000, v57
	v_pk_mul_f32 v[4:5], v[8:9], v[4:5]
	v_lshlrev_b32_e32 v8, 16, v58
	v_cvt_pk_bf16_f32 v57, v4, v5
	v_lshlrev_b32_e32 v4, 16, v6
	v_and_b32_e32 v5, 0xffff0000, v6
	v_and_b32_e32 v9, 0xffff0000, v58
	v_pk_mul_f32 v[4:5], v[8:9], v[4:5]
	v_lshlrev_b32_e32 v6, 16, v59
	v_cvt_pk_bf16_f32 v58, v4, v5
	v_lshlrev_b32_e32 v4, 16, v7
	v_and_b32_e32 v5, 0xffff0000, v7
	v_and_b32_e32 v7, 0xffff0000, v59
	v_pk_mul_f32 v[4:5], v[6:7], v[4:5]
	s_nop 0
	v_cvt_pk_bf16_f32 v59, v4, v5
	v_lshlrev_b64 v[4:5], 11, v[90:91]
	v_lshl_add_u64 v[6:7], v[76:77], 0, v[4:5]
	global_store_dwordx4 v[6:7], v[56:59], off sc0 sc1
	s_nop 1
	ds_read_b128 v[6:9], v55 offset:2304
	s_waitcnt vmcnt(3)
	v_lshlrev_b32_e32 v58, 16, v60
	v_and_b32_e32 v59, 0xffff0000, v60
	s_waitcnt vmcnt(2)
	v_lshlrev_b32_e32 v60, 16, v64
	s_waitcnt lgkmcnt(0)
	v_lshlrev_b32_e32 v56, 16, v6
	v_and_b32_e32 v57, 0xffff0000, v6
	v_pk_mul_f32 v[56:57], v[58:59], v[56:57]
	v_lshlrev_b32_e32 v6, 16, v7
	v_and_b32_e32 v7, 0xffff0000, v7
	v_lshlrev_b32_e32 v58, 16, v61
	v_and_b32_e32 v59, 0xffff0000, v61
	v_pk_mul_f32 v[6:7], v[58:59], v[6:7]
	v_cvt_pk_bf16_f32 v56, v56, v57
	v_cvt_pk_bf16_f32 v57, v6, v7
	v_lshlrev_b32_e32 v6, 16, v8
	v_and_b32_e32 v7, 0xffff0000, v8
	v_lshlrev_b32_e32 v58, 16, v62
	v_and_b32_e32 v59, 0xffff0000, v62
	v_pk_mul_f32 v[6:7], v[58:59], v[6:7]
	v_lshlrev_b32_e32 v8, 16, v63
	v_cvt_pk_bf16_f32 v58, v6, v7
	v_lshlrev_b32_e32 v6, 16, v9
	v_and_b32_e32 v7, 0xffff0000, v9
	v_and_b32_e32 v9, 0xffff0000, v63
	v_pk_mul_f32 v[6:7], v[8:9], v[6:7]
	v_and_b32_e32 v61, 0xffff0000, v64
	v_cvt_pk_bf16_f32 v59, v6, v7
	v_lshlrev_b64 v[6:7], 11, v[72:73]
	v_lshl_add_u64 v[8:9], v[76:77], 0, v[6:7]
	global_store_dwordx4 v[8:9], v[56:59], off sc0 sc1
	s_nop 1
	ds_read_b128 v[56:59], v55 offset:3456
	s_waitcnt lgkmcnt(0)
	v_lshlrev_b32_e32 v8, 16, v56
	v_and_b32_e32 v9, 0xffff0000, v56
	v_pk_mul_f32 v[8:9], v[60:61], v[8:9]
	v_lshlrev_b32_e32 v60, 16, v65
	v_cvt_pk_bf16_f32 v56, v8, v9
	v_lshlrev_b32_e32 v8, 16, v57
	v_and_b32_e32 v9, 0xffff0000, v57
	v_and_b32_e32 v61, 0xffff0000, v65
	v_pk_mul_f32 v[8:9], v[60:61], v[8:9]
	v_lshlrev_b32_e32 v60, 16, v66
	v_cvt_pk_bf16_f32 v57, v8, v9
	v_lshlrev_b32_e32 v8, 16, v58
	v_and_b32_e32 v9, 0xffff0000, v58
	v_and_b32_e32 v61, 0xffff0000, v66
	v_pk_mul_f32 v[8:9], v[60:61], v[8:9]
	v_lshlrev_b32_e32 v60, 16, v67
	v_cvt_pk_bf16_f32 v58, v8, v9
	v_lshlrev_b32_e32 v8, 16, v59
	v_and_b32_e32 v9, 0xffff0000, v59
	v_and_b32_e32 v61, 0xffff0000, v67
	v_pk_mul_f32 v[8:9], v[60:61], v[8:9]
	s_nop 0
	v_cvt_pk_bf16_f32 v59, v8, v9
	v_lshlrev_b64 v[8:9], 11, v[74:75]
	v_lshl_add_u64 v[60:61], v[76:77], 0, v[8:9]
	global_store_dwordx4 v[60:61], v[56:59], off sc0 sc1
	s_nop 1
	s_cbranch_vccnz .LBB0_500
	s_and_b64 vcc, exec, s[8:9]
	s_mov_b64 s[6:7], -1
	s_cbranch_vccnz .LBB0_579
	v_max_f32_e32 v2, v85, v85
	v_max_f32_e32 v54, v19, v19
	v_max_f32_e32 v2, v54, v2
	v_sub_f32_e32 v19, v19, v2
	v_sub_f32_e32 v2, v85, v2
	v_exp_f32_e32 v19, v19
	v_exp_f32_e32 v2, v2
	s_nop 0
	v_fmac_f32_e32 v2, v84, v19
	v_div_scale_f32 v54, s[6:7], v2, v2, v19
	v_rcp_f32_e32 v56, v54
	v_div_scale_f32 v57, vcc, v19, v2, v19
	s_mov_b64 s[6:7], 0
	v_fma_f32 v58, -v54, v56, 1.0
	v_fmac_f32_e32 v56, v58, v56
	v_mul_f32_e32 v58, v57, v56
	v_fma_f32 v59, -v54, v58, v57
	v_fmac_f32_e32 v58, v59, v56
	v_fma_f32 v54, -v54, v58, v57
	v_div_fmas_f32 v54, v54, v56, v58
	v_div_fixup_f32 v54, v54, v2, v19
